# merge / outproj: rank-static XCD mapping (one atomic per workgroup and phase gives the rank on its XCD, items rank + k*nloc) instead of a per-item queue fetch; flat fallback kept
# baseline (speedup 1.0000x reference)
; DI void phase_merge(const Params& p, int l, char* smem, int tid) {
;     ...
;   for (int it = (dyn ? fetch_item(qc, smem) : (int)blockIdx.x); it < 544 * 8; it = (dyn ? fetch_item(qc, smem) : it + (int)gridDim.x)) {
;     const int mt = it >> 3, nt = it & 7, m0 = mt * 64, n0 = nt * 128;
;     if (l == 1 && (mt % 68) < 4) continue;
.LBB0_1140:
	s_or_b64 exec, exec, s[0:1]
	v_readlane_b32 s2, v254, 17
	v_readlane_b32 s3, v254, 18
	v_mov_b32_e32 v0, v206
	s_andn2_b64 vcc, exec, s[2:3]
	v_cndmask_b32_e64 v2, 0, 1, s[2:3]
	v_cmp_ne_u32_e64 s[0:1], 1, v2
	v_mov_b32_e32 v149, s48
	s_waitcnt lgkmcnt(0)
	s_barrier
	v_readlane_b32 s18, v254, 19
	v_and_b32_e32 v147, 63, v206
	v_lshrrev_b32_e32 v149, 6, v206
	v_lshrrev_b32_e32 v151, 3, v147
	v_lshl_add_u32 v151, v149, 5, v151
	v_lshlrev_b32_e32 v151, 11, v151
	v_and_b32_e32 v153, 7, v147
	v_lshrrev_b32_e32 v147, 4, v147
	v_xor_b32_e32 v153, v153, v147
	v_lshl_or_b32 v200, v153, 4, v151
	v_xor_b32_e32 v201, 64, v200
	v_add_u32_e32 v201, 16384, v201
	v_add_u32_e32 v202, 32768, v200
	v_add_u32_e32 v203, 32768, v201
	v_and_b32_e32 v147, 63, v206
	v_lshrrev_b32_e32 v149, 6, v206
	v_lshrrev_b32_e32 v151, 3, v147
	v_lshl_add_u32 v151, v149, 5, v151
	v_lshlrev_b32_e32 v151, 9, v151
	v_and_b32_e32 v153, 7, v147
	v_lshrrev_b32_e32 v147, 4, v147
	v_xor_b32_e32 v153, v153, v147
	v_lshl_or_b32 v130, v153, 4, v151
	v_xor_b32_e32 v131, 64, v130
	v_add_u32_e32 v131, 4096, v131
	v_add_u32_e32 v132, 8192, v130
	v_add_u32_e32 v133, 8192, v131
	v_lshrrev_b32_e32 v204, 6, v206
	v_and_b32_e32 v147, 31, v206
	v_bfe_u32 v149, v206, 5, 1
	v_bfe_u32 v151, v147, 1, 3
	v_xor_b32_e32 v151, v151, v149
	v_lshlrev_b32_e32 v151, 4, v151
	v_lshl_or_b32 v151, v147, 7, v151
	v_lshrrev_b32_e32 v153, 7, v206
	v_lshl_add_u32 v138, v153, 13, v151
	v_bfe_u32 v153, v206, 6, 1
	v_lshl_add_u32 v142, v153, 13, v151
	v_add_u32_e32 v142, 0x4000, v142
	v_xor_b32_e32 v139, 32, v138
	v_xor_b32_e32 v143, 32, v142
	v_xor_b32_e32 v140, 64, v138
	v_xor_b32_e32 v144, 64, v142
	v_xor_b32_e32 v141, 96, v138
	v_xor_b32_e32 v145, 96, v142
	v_and_b32_e32 v147, 31, v206
	v_lshrrev_b32_e32 v149, 7, v206
	v_lshl_add_u32 v147, v149, 6, v147
	v_lshlrev_b32_e32 v147, 11, v147
	v_bfe_u32 v149, v206, 6, 1
	v_lshlrev_b32_e32 v149, 7, v149
	v_bfe_u32 v151, v206, 5, 1
	v_lshl_or_b32 v149, v151, 3, v149
	v_or_b32_e32 v146, v147, v149
	v_lshrrev_b32_e32 v147, 6, v206
	v_mul_u32_u24_e32 v147, 0x2400, v147
	v_and_b32_e32 v149, 31, v206
	v_mul_u32_u24_e32 v149, 0x90, v149
	v_bfe_u32 v151, v206, 5, 1
	v_lshl_add_u32 v149, v151, 3, v149
	v_add_u32_e32 v134, v147, v149
	v_bfe_u32 v149, v206, 3, 3
	v_mul_u32_u24_e32 v149, 0x90, v149
	v_and_b32_e32 v151, 7, v206
	v_lshl_add_u32 v149, v151, 4, v149
	v_add_u32_e32 v135, v147, v149
	v_bfe_u32 v147, v206, 3, 3
	v_lshrrev_b32_e32 v149, 7, v206
	v_lshl_add_u32 v147, v149, 6, v147
	v_mul_u32_u24_e32 v147, 0x800, v147
	v_bfe_u32 v149, v206, 6, 1
	v_lshlrev_b32_e32 v149, 7, v149
	v_and_b32_e32 v151, 7, v206
	v_lshl_or_b32 v149, v151, 4, v149
	v_add_u32_e32 v136, v147, v149
	v_readfirstlane_b32 s10, v204
	s_lshl_b32 s10, s10, 12
	s_lshl_b32 s6, s18, 23
	s_add_u32 s14, s96, 0x1b720000
	s_addc_u32 s15, s97, 0
	s_add_u32 s14, s14, s6
	s_addc_u32 s15, s15, 0
	s_lshl_b32 s6, s18, 21
	s_add_u32 s16, s96, 0x1c800000
	s_addc_u32 s17, s97, 0
	s_add_u32 s16, s16, s6
	s_addc_u32 s17, s17, 0
	s_mov_b32 s12, s48
	s_mov_b32 s94, 0
	v_mov_b32_e32 v153, 0x125f0
	ds_read_b32 v149, v153 offset:16
	ds_read_b32 v147, v153 offset:20
	s_waitcnt lgkmcnt(0)
	v_readfirstlane_b32 s6, v147
	s_cmp_eq_u32 s6, 8
	s_cbranch_scc0 .Lmgr_flat
	s_cmp_eq_u32 s10, 0
	s_cbranch_scc0 .Lmgr_wait
	s_mov_b64 s[6:7], exec
	s_mov_b64 exec, 1
	s_getreg_b32 s8, hwreg(HW_REG_XCC_ID, 0, 4)
	s_lshl_b32 s8, s8, 8
	s_lshl_b32 s9, s18, 11
	s_add_u32 s8, s8, s9
	s_add_u32 s8, s8, 0x1da5e000
	s_add_u32 s8, s96, s8
	s_addc_u32 s9, s97, 0
	v_mov_b32_e32 v147, 1
	v_mov_b32_e32 v151, 0
	global_atomic_add v151, v151, v147, s[8:9] sc0
	s_waitcnt vmcnt(0)
	ds_write_b32 v153, v151
	s_waitcnt lgkmcnt(0)
	s_mov_b64 exec, s[6:7]
.Lmgr_wait:
	s_barrier
	ds_read_b32 v151, v153
	s_waitcnt lgkmcnt(0)
	v_readfirstlane_b32 s12, v151
	v_readfirstlane_b32 s94, v149
.Lmgr_flat:
.Lmg_item:
	s_cmp_eq_u32 s94, 0
	s_cbranch_scc1 .Lmg_flat
	s_barrier
	s_getreg_b32 s8, hwreg(HW_REG_XCC_ID, 0, 4)
	s_lshr_b32 s6, s12, 3
	s_lshl_b32 s6, s6, 3
	s_add_u32 s6, s6, s8
	s_cmp_eq_u32 s18, 0
	s_cbranch_scc0 .Lmgx_l1
	s_cmpk_lt_u32 s12, 0x110
	s_cbranch_scc0 .Lmg_done
	s_and_b32 s13, s12, 7
	s_mov_b32 s19, s6
	s_branch .Lmg_decoded
.Lmgx_l1:
	s_cmpk_lt_u32 s12, 0x100
	s_cbranch_scc0 .Lmg_done
	s_and_b32 s13, s12, 7
	s_lshr_b32 s7, s6, 5
	s_mul_i32 s7, s7, 34
	s_and_b32 s6, s6, 31
	s_add_u32 s19, s7, s6
	s_add_u32 s19, s19, 2
	s_branch .Lmg_decoded

; DI void phase_merge(const Params& p, int l, char* smem, int tid) {
;     ...
;     f32x16 accT[1][2]; zero_acc<1>(accT);
; #pragma unroll 1
;     for (int i = 0; i < 4; i++) {
;       if ((ZERO_MASK >> i) & 1) continue;
;       unsigned sg[2][8];
;       {
;         f32x16 m[1][2]; zero_acc<1>(m);
;         gemm_main<1>(p.xn + (size_t)m0 * 1024, 1024, p.WtM + (size_t)l * 4096 * 1024 + ((size_t)i * 1024 + n0) * 1024, 1024, 1024, m, s, tid);
.Lmg_decoded:
	s_lshr_b32 s3, s19, 14
	s_lshl_b32 s2, s19, 18
	s_add_u32 s2, s96, s2
	s_addc_u32 s3, s97, s3
	s_lshl_b32 s19, s13, 18
.Lmg_again:
	v_mov_b32_e32 v2, 0
	v_mov_b32_e32 v3, 0
	v_mov_b32_e32 v4, 0
	v_mov_b32_e32 v5, 0
	v_mov_b32_e32 v6, 0
	v_mov_b32_e32 v7, 0
	v_mov_b32_e32 v8, 0
	v_mov_b32_e32 v9, 0
	v_mov_b32_e32 v10, 0
	v_mov_b32_e32 v11, 0
	v_mov_b32_e32 v12, 0
	v_mov_b32_e32 v13, 0
	v_mov_b32_e32 v14, 0
	v_mov_b32_e32 v15, 0
	v_mov_b32_e32 v16, 0
	v_mov_b32_e32 v17, 0
	v_mov_b32_e32 v18, 0
	v_mov_b32_e32 v19, 0
	v_mov_b32_e32 v20, 0
	v_mov_b32_e32 v21, 0
	v_mov_b32_e32 v22, 0
	v_mov_b32_e32 v23, 0
	v_mov_b32_e32 v24, 0
	v_mov_b32_e32 v25, 0
	v_mov_b32_e32 v26, 0
	v_mov_b32_e32 v27, 0
	v_mov_b32_e32 v28, 0
	v_mov_b32_e32 v29, 0
	v_mov_b32_e32 v30, 0
	v_mov_b32_e32 v31, 0
	v_mov_b32_e32 v32, 0
	v_mov_b32_e32 v33, 0
	v_mov_b32_e32 v34, 0
	v_mov_b32_e32 v35, 0
	v_mov_b32_e32 v36, 0
	v_mov_b32_e32 v37, 0
	v_mov_b32_e32 v38, 0
	v_mov_b32_e32 v39, 0
	v_mov_b32_e32 v40, 0
	v_mov_b32_e32 v41, 0
	v_mov_b32_e32 v42, 0
	v_mov_b32_e32 v43, 0
	v_mov_b32_e32 v44, 0
	v_mov_b32_e32 v45, 0
	v_mov_b32_e32 v46, 0
	v_mov_b32_e32 v47, 0
	v_mov_b32_e32 v48, 0
	v_mov_b32_e32 v49, 0
	v_mov_b32_e32 v50, 0
	v_mov_b32_e32 v51, 0
	v_mov_b32_e32 v52, 0
	v_mov_b32_e32 v53, 0
	v_mov_b32_e32 v54, 0
	v_mov_b32_e32 v55, 0
	v_mov_b32_e32 v56, 0
	v_mov_b32_e32 v57, 0
	v_mov_b32_e32 v58, 0
	v_mov_b32_e32 v59, 0
	v_mov_b32_e32 v60, 0
	v_mov_b32_e32 v61, 0
	v_mov_b32_e32 v62, 0
	v_mov_b32_e32 v63, 0
	v_mov_b32_e32 v64, 0
	v_mov_b32_e32 v65, 0
	s_mov_b32 s13, 0
	s_mov_b32 s4, s2
	s_mov_b32 s5, s3
	s_add_u32 s8, s14, s19
	s_addc_u32 s9, s15, 0
	s_add_u32 m0, s10, 0x0
	s_nop 0
	global_load_lds_dwordx4 v200, s[4:5]
	s_add_u32 m0, s10, 0x400
	s_nop 0
	global_load_lds_dwordx4 v201, s[4:5]
	s_add_u32 m0, s10, 0x800
	s_nop 0
	global_load_lds_dwordx4 v202, s[4:5]
	s_add_u32 m0, s10, 0xc00
	s_nop 0
	global_load_lds_dwordx4 v203, s[4:5]
	s_add_u32 m0, s10, 0x4000
	s_nop 0
	global_load_lds_dwordx4 v200, s[8:9]
	s_add_u32 m0, s10, 0x4400
	s_nop 0
	global_load_lds_dwordx4 v201, s[8:9]
	s_add_u32 m0, s10, 0x4800
	s_nop 0
	global_load_lds_dwordx4 v202, s[8:9]
	s_add_u32 m0, s10, 0x4c00
	s_nop 0
	global_load_lds_dwordx4 v203, s[8:9]
	s_add_u32 s4, s4, 128
	s_addc_u32 s5, s5, 0
	s_add_u32 s8, s8, 128
	s_addc_u32 s9, s9, 0

; DI float bflo(unsigned v) { return __uint_as_float(v << 16); }
; DI float bfhi(unsigned v) { return __uint_as_float(v & 0xffff0000u); }
; DI void phase_merge(const Params& p, int l, char* smem, int tid) {
;     ...
; #pragma unroll
;       for (int b2 = 0; b2 < 2; b2++)
; #pragma unroll
;         for (int e = 0; e < 8; e++) { accT[0][b2][2 * e] += bflo(sg[b2][e]) * t[0][b2][2 * e]; accT[0][b2][2 * e + 1] += bfhi(sg[b2][e]) * t[0][b2][2 * e + 1]; }
.Lmgt_kdone:
	s_nop 7
	s_nop 7
	v_lshlrev_b32_e32 v147, 16, v156
	v_and_b32_e32 v149, 0xffff0000, v156
	v_fmac_f32_e32 v2, v147, v66
	v_fmac_f32_e32 v3, v149, v67
	v_lshlrev_b32_e32 v151, 16, v157
	v_and_b32_e32 v153, 0xffff0000, v157
	v_fmac_f32_e32 v4, v151, v68
	v_fmac_f32_e32 v5, v153, v69
	v_lshlrev_b32_e32 v147, 16, v158
	v_and_b32_e32 v149, 0xffff0000, v158
	v_fmac_f32_e32 v6, v147, v70
	v_fmac_f32_e32 v7, v149, v71
	v_lshlrev_b32_e32 v151, 16, v159
	v_and_b32_e32 v153, 0xffff0000, v159
	v_fmac_f32_e32 v8, v151, v72
	v_fmac_f32_e32 v9, v153, v73
	v_lshlrev_b32_e32 v147, 16, v160
	v_and_b32_e32 v149, 0xffff0000, v160
	v_fmac_f32_e32 v10, v147, v74
	v_fmac_f32_e32 v11, v149, v75
	v_lshlrev_b32_e32 v151, 16, v161
	v_and_b32_e32 v153, 0xffff0000, v161
	v_fmac_f32_e32 v12, v151, v76
	v_fmac_f32_e32 v13, v153, v77
	v_lshlrev_b32_e32 v147, 16, v162
	v_and_b32_e32 v149, 0xffff0000, v162
	v_fmac_f32_e32 v14, v147, v78
	v_fmac_f32_e32 v15, v149, v79
	v_lshlrev_b32_e32 v151, 16, v163
	v_and_b32_e32 v153, 0xffff0000, v163
	v_fmac_f32_e32 v16, v151, v80
	v_fmac_f32_e32 v17, v153, v81
	v_lshlrev_b32_e32 v147, 16, v164
	v_and_b32_e32 v149, 0xffff0000, v164
	v_fmac_f32_e32 v18, v147, v82
	v_fmac_f32_e32 v19, v149, v83
	v_lshlrev_b32_e32 v151, 16, v165
	v_and_b32_e32 v153, 0xffff0000, v165
	v_fmac_f32_e32 v20, v151, v84
	v_fmac_f32_e32 v21, v153, v85
	v_lshlrev_b32_e32 v147, 16, v166
	v_and_b32_e32 v149, 0xffff0000, v166
	v_fmac_f32_e32 v22, v147, v86
	v_fmac_f32_e32 v23, v149, v87
	v_lshlrev_b32_e32 v151, 16, v167
	v_and_b32_e32 v153, 0xffff0000, v167
	v_fmac_f32_e32 v24, v151, v88
	v_fmac_f32_e32 v25, v153, v89
	v_lshlrev_b32_e32 v147, 16, v168
	v_and_b32_e32 v149, 0xffff0000, v168
	v_fmac_f32_e32 v26, v147, v90
	v_fmac_f32_e32 v27, v149, v91
	v_lshlrev_b32_e32 v151, 16, v169
	v_and_b32_e32 v153, 0xffff0000, v169
	v_fmac_f32_e32 v28, v151, v92
	v_fmac_f32_e32 v29, v153, v93
	v_lshlrev_b32_e32 v147, 16, v170
	v_and_b32_e32 v149, 0xffff0000, v170
	v_fmac_f32_e32 v30, v147, v94
	v_fmac_f32_e32 v31, v149, v95
	v_lshlrev_b32_e32 v151, 16, v171
	v_and_b32_e32 v153, 0xffff0000, v171
	v_fmac_f32_e32 v32, v151, v96
	v_fmac_f32_e32 v33, v153, v97
	v_lshlrev_b32_e32 v147, 16, v172
	v_and_b32_e32 v149, 0xffff0000, v172
	v_fmac_f32_e32 v34, v147, v98
	v_fmac_f32_e32 v35, v149, v99
	v_lshlrev_b32_e32 v151, 16, v173
	v_and_b32_e32 v153, 0xffff0000, v173
	v_fmac_f32_e32 v36, v151, v100
	v_fmac_f32_e32 v37, v153, v101
	v_lshlrev_b32_e32 v147, 16, v174
	v_and_b32_e32 v149, 0xffff0000, v174
	v_fmac_f32_e32 v38, v147, v102
	v_fmac_f32_e32 v39, v149, v103
	v_lshlrev_b32_e32 v151, 16, v175
	v_and_b32_e32 v153, 0xffff0000, v175
	v_fmac_f32_e32 v40, v151, v104
	v_fmac_f32_e32 v41, v153, v105
	v_lshlrev_b32_e32 v147, 16, v176
	v_and_b32_e32 v149, 0xffff0000, v176
	v_fmac_f32_e32 v42, v147, v106
	v_fmac_f32_e32 v43, v149, v107
	v_lshlrev_b32_e32 v151, 16, v177
	v_and_b32_e32 v153, 0xffff0000, v177
	v_fmac_f32_e32 v44, v151, v108
	v_fmac_f32_e32 v45, v153, v109
	v_lshlrev_b32_e32 v147, 16, v178
	v_and_b32_e32 v149, 0xffff0000, v178
	v_fmac_f32_e32 v46, v147, v110
	v_fmac_f32_e32 v47, v149, v111
	v_lshlrev_b32_e32 v151, 16, v179
	v_and_b32_e32 v153, 0xffff0000, v179
	v_fmac_f32_e32 v48, v151, v112
	v_fmac_f32_e32 v49, v153, v113
	v_lshlrev_b32_e32 v147, 16, v180
	v_and_b32_e32 v149, 0xffff0000, v180
	v_fmac_f32_e32 v50, v147, v114
	v_fmac_f32_e32 v51, v149, v115
	v_lshlrev_b32_e32 v151, 16, v181
	v_and_b32_e32 v153, 0xffff0000, v181
	v_fmac_f32_e32 v52, v151, v116
	v_fmac_f32_e32 v53, v153, v117
	v_lshlrev_b32_e32 v147, 16, v182
	v_and_b32_e32 v149, 0xffff0000, v182
	v_fmac_f32_e32 v54, v147, v118
	v_fmac_f32_e32 v55, v149, v119
	v_lshlrev_b32_e32 v151, 16, v183
	v_and_b32_e32 v153, 0xffff0000, v183
	v_fmac_f32_e32 v56, v151, v120
	v_fmac_f32_e32 v57, v153, v121
	v_lshlrev_b32_e32 v147, 16, v184
	v_and_b32_e32 v149, 0xffff0000, v184
	v_fmac_f32_e32 v58, v147, v122
	v_fmac_f32_e32 v59, v149, v123
	v_lshlrev_b32_e32 v151, 16, v185
	v_and_b32_e32 v153, 0xffff0000, v185
	v_fmac_f32_e32 v60, v151, v124
	v_fmac_f32_e32 v61, v153, v125
	v_lshlrev_b32_e32 v147, 16, v186
	v_and_b32_e32 v149, 0xffff0000, v186
	v_fmac_f32_e32 v62, v147, v126
	v_fmac_f32_e32 v63, v149, v127
	v_lshlrev_b32_e32 v151, 16, v187
	v_and_b32_e32 v153, 0xffff0000, v187
	v_fmac_f32_e32 v64, v151, v128
	v_fmac_f32_e32 v65, v153, v129
	s_add_u32 s13, s13, 1
	s_cmp_lt_u32 s13, 8
	s_cbranch_scc1 .Lmg_seg
; DI u16 f2bf(float x) { return (u16)(pack2(x, 0.f) & 0xffffu); }
; DI int crow(int i, int h) { return (i & 3) + 8 * (i >> 2) + 4 * h; }
; DI void phase_merge(const Params& p, int l, char* smem, int tid) {
;     ...
; #pragma unroll
;     for (int nb = 0; nb < 2; nb++) {
;       const int rowb = m0 + wm * 32, col = n0 + wn * 64 + nb * 32 + r;
; #pragma unroll
;       for (int i = 0; i < 16; i++) ACC[(size_t)(rowb + crow(i, h)) * 1024 + col] = f2bf(accT[0][nb][i]);
;     }
	s_sub_u32 s6, s2, s96
	s_subb_u32 s7, s3, s97
	s_add_u32 s6, s6, s90
	s_addc_u32 s7, s7, s91
	s_lshr_b32 s8, s19, 10
	s_add_u32 s6, s6, s8
	s_addc_u32 s7, s7, 0
	v_cvt_pk_bf16_f32 v66, v2, v3
	v_cvt_pk_bf16_f32 v67, v4, v5
	ds_write_b64 v134, v[66:67] offset:0
	v_cvt_pk_bf16_f32 v68, v6, v7
	v_cvt_pk_bf16_f32 v69, v8, v9
	ds_write_b64 v134, v[68:69] offset:16
	v_cvt_pk_bf16_f32 v70, v10, v11
	v_cvt_pk_bf16_f32 v71, v12, v13
	ds_write_b64 v134, v[70:71] offset:32
	v_cvt_pk_bf16_f32 v72, v14, v15
	v_cvt_pk_bf16_f32 v73, v16, v17
	ds_write_b64 v134, v[72:73] offset:48
	v_cvt_pk_bf16_f32 v66, v18, v19
	v_cvt_pk_bf16_f32 v67, v20, v21
	ds_write_b64 v134, v[66:67] offset:64
	v_cvt_pk_bf16_f32 v68, v22, v23
	v_cvt_pk_bf16_f32 v69, v24, v25
	ds_write_b64 v134, v[68:69] offset:80
	v_cvt_pk_bf16_f32 v70, v26, v27
	v_cvt_pk_bf16_f32 v71, v28, v29
	ds_write_b64 v134, v[70:71] offset:96
	v_cvt_pk_bf16_f32 v72, v30, v31
	v_cvt_pk_bf16_f32 v73, v32, v33
	ds_write_b64 v134, v[72:73] offset:112
	v_cvt_pk_bf16_f32 v66, v34, v35
	v_cvt_pk_bf16_f32 v67, v36, v37
	ds_write_b64 v134, v[66:67] offset:4608
	v_cvt_pk_bf16_f32 v68, v38, v39
	v_cvt_pk_bf16_f32 v69, v40, v41
	ds_write_b64 v134, v[68:69] offset:4624
	v_cvt_pk_bf16_f32 v70, v42, v43
	v_cvt_pk_bf16_f32 v71, v44, v45
	ds_write_b64 v134, v[70:71] offset:4640
	v_cvt_pk_bf16_f32 v72, v46, v47
	v_cvt_pk_bf16_f32 v73, v48, v49
	ds_write_b64 v134, v[72:73] offset:4656
	v_cvt_pk_bf16_f32 v66, v50, v51
	v_cvt_pk_bf16_f32 v67, v52, v53
	ds_write_b64 v134, v[66:67] offset:4672
	v_cvt_pk_bf16_f32 v68, v54, v55
	v_cvt_pk_bf16_f32 v69, v56, v57
	ds_write_b64 v134, v[68:69] offset:4688
	v_cvt_pk_bf16_f32 v70, v58, v59
	v_cvt_pk_bf16_f32 v71, v60, v61
	ds_write_b64 v134, v[70:71] offset:4704
	v_cvt_pk_bf16_f32 v72, v62, v63
	v_cvt_pk_bf16_f32 v73, v64, v65
	ds_write_b64 v134, v[72:73] offset:4720
	ds_read_b128 v[74:77], v135 offset:0
	ds_read_b128 v[78:81], v135 offset:1152
	ds_read_b128 v[82:85], v135 offset:2304
	ds_read_b128 v[86:89], v135 offset:3456
	ds_read_b128 v[90:93], v135 offset:4608
	ds_read_b128 v[94:97], v135 offset:5760
	ds_read_b128 v[98:101], v135 offset:6912
	ds_read_b128 v[102:105], v135 offset:8064
	s_waitcnt lgkmcnt(7)
	global_store_dwordx4 v136, v[74:77], s[6:7]
	s_add_u32 s6, s6, 0x4000
	s_addc_u32 s7, s7, 0
	s_waitcnt lgkmcnt(6)
	global_store_dwordx4 v136, v[78:81], s[6:7]
	s_add_u32 s6, s6, 0x4000
	s_addc_u32 s7, s7, 0
	s_waitcnt lgkmcnt(5)
	global_store_dwordx4 v136, v[82:85], s[6:7]
	s_add_u32 s6, s6, 0x4000
	s_addc_u32 s7, s7, 0
	s_waitcnt lgkmcnt(4)
	global_store_dwordx4 v136, v[86:89], s[6:7]
	s_add_u32 s6, s6, 0x4000
	s_addc_u32 s7, s7, 0
	s_waitcnt lgkmcnt(3)
	global_store_dwordx4 v136, v[90:93], s[6:7]
	s_add_u32 s6, s6, 0x4000
	s_addc_u32 s7, s7, 0
	s_waitcnt lgkmcnt(2)
	global_store_dwordx4 v136, v[94:97], s[6:7]
	s_add_u32 s6, s6, 0x4000
	s_addc_u32 s7, s7, 0
	s_waitcnt lgkmcnt(1)
	global_store_dwordx4 v136, v[98:101], s[6:7]
	s_add_u32 s6, s6, 0x4000
	s_addc_u32 s7, s7, 0
	s_waitcnt lgkmcnt(0)
	global_store_dwordx4 v136, v[102:105], s[6:7]
	s_cmp_eq_u32 s94, 0
	s_cbranch_scc1 .Lmg_lbflat
	s_add_u32 s12, s12, s94
	s_branch .Lmg_item
.Lmg_lbflat:
	s_cmp_eq_u32 s18, 0
	s_cbranch_scc1 .Lmg_item
	s_add_u32 s12, s12, s49
	s_branch .Lmg_item

; DI void phase_outproj(const Params& p, int l, char* smem, int tid) {
;     ...
;   for (int it = (dyn ? fetch_item(qc, smem) : (int)blockIdx.x); it < 272 * 8; it = (dyn ? fetch_item(qc, smem) : it + (int)gridDim.x)) {
;     const int mt = it >> 3, nt = it & 7, m0 = mt * 128, n0 = nt * 128;
;     if (l == 1 && (mt % 34) < 2) continue;
.LBB0_1221:
	s_or_b64 exec, exec, s[4:5]
	v_mov_b32_e32 v0, v206
	s_and_b64 vcc, exec, s[0:1]
	v_mov_b32_e32 v146, s48
	s_waitcnt lgkmcnt(0)
	s_barrier
	v_readlane_b32 s18, v254, 19
	v_and_b32_e32 v112, 63, v206
	v_lshrrev_b32_e32 v113, 6, v206
	v_lshrrev_b32_e32 v114, 3, v112
	v_lshl_add_u32 v114, v113, 5, v114
	v_lshlrev_b32_e32 v114, 11, v114
	v_and_b32_e32 v115, 7, v112
	v_lshrrev_b32_e32 v112, 4, v112
	v_xor_b32_e32 v115, v115, v112
	v_lshl_or_b32 v98, v115, 4, v114
	v_xor_b32_e32 v99, 64, v98
	v_add_u32_e32 v99, 16384, v99
	v_add_u32_e32 v100, 32768, v98
	v_add_u32_e32 v101, 32768, v99
	v_lshrrev_b32_e32 v156, 6, v206
	v_and_b32_e32 v112, 31, v206
	v_bfe_u32 v113, v206, 5, 1
	v_bfe_u32 v114, v112, 1, 3
	v_xor_b32_e32 v114, v114, v113
	v_lshlrev_b32_e32 v114, 4, v114
	v_lshl_or_b32 v114, v112, 7, v114
	v_lshrrev_b32_e32 v115, 7, v206
	v_lshl_add_u32 v102, v115, 13, v114
	v_bfe_u32 v115, v206, 6, 1
	v_lshl_add_u32 v106, v115, 13, v114
	v_add_u32_e32 v106, 0x4000, v106
	v_xor_b32_e32 v103, 32, v102
	v_xor_b32_e32 v107, 32, v106
	v_xor_b32_e32 v104, 64, v102
	v_xor_b32_e32 v108, 64, v106
	v_xor_b32_e32 v105, 96, v102
	v_xor_b32_e32 v109, 96, v106
	v_and_b32_e32 v112, 31, v206
	v_lshrrev_b32_e32 v113, 7, v206
	v_lshl_add_u32 v112, v113, 6, v112
	v_lshlrev_b32_e32 v112, 11, v112
	v_bfe_u32 v113, v206, 6, 1
	v_bfe_u32 v114, v206, 5, 1
	v_lshlrev_b32_e32 v115, 7, v113
	v_lshl_or_b32 v115, v114, 3, v115
	v_or_b32_e32 v110, v112, v115
	v_lshlrev_b32_e32 v111, 8, v113
	v_lshl_or_b32 v111, v114, 4, v111
	v_lshrrev_b32_e32 v112, 6, v206
	v_mul_u32_u24_e32 v112, 0x2400, v112
	v_and_b32_e32 v113, 31, v206
	v_mul_u32_u24_e32 v113, 0x90, v113
	v_bfe_u32 v114, v206, 5, 1
	v_lshl_add_u32 v113, v114, 3, v113
	v_add_u32_e32 v164, v112, v113
	v_bfe_u32 v113, v206, 3, 3
	v_mul_u32_u24_e32 v113, 0x90, v113
	v_and_b32_e32 v114, 7, v206
	v_lshl_add_u32 v113, v114, 4, v113
	v_add_u32_e32 v165, v112, v113
	v_bfe_u32 v112, v206, 3, 3
	v_lshrrev_b32_e32 v113, 7, v206
	v_lshl_add_u32 v112, v113, 6, v112
	v_mul_u32_u24_e32 v112, 0x800, v112
	v_bfe_u32 v113, v206, 6, 1
	v_lshlrev_b32_e32 v113, 7, v113
	v_and_b32_e32 v114, 7, v206
	v_lshl_or_b32 v113, v114, 4, v113
	v_add_u32_e32 v166, v112, v113
	v_readfirstlane_b32 s10, v156
	s_lshl_b32 s10, s10, 12
	s_lshl_b32 s6, s18, 21
	s_add_u32 s14, s96, 0x1cc00000
	s_addc_u32 s15, s97, 0
	s_add_u32 s14, s14, s6
	s_addc_u32 s15, s15, 0
	s_mov_b32 s12, s48
	s_mov_b32 s94, 0
	v_mov_b32_e32 v115, 0x125f0
	ds_read_b32 v113, v115 offset:16
	ds_read_b32 v112, v115 offset:20
	s_waitcnt lgkmcnt(0)
	v_readfirstlane_b32 s6, v112
	s_cmp_eq_u32 s6, 8
	s_cbranch_scc0 .Lopr_flat
	s_cmp_eq_u32 s10, 0
	s_cbranch_scc0 .Lopr_wait
	s_mov_b64 s[6:7], exec
	s_mov_b64 exec, 1
	s_getreg_b32 s8, hwreg(HW_REG_XCC_ID, 0, 4)
	s_lshl_b32 s8, s8, 8
	s_lshl_b32 s9, s18, 11
	s_add_u32 s8, s8, s9
	s_add_u32 s8, s8, 0x1da5f000
	s_add_u32 s8, s96, s8
	s_addc_u32 s9, s97, 0
	v_mov_b32_e32 v112, 1
	v_mov_b32_e32 v114, 0
	global_atomic_add v114, v114, v112, s[8:9] sc0
	s_waitcnt vmcnt(0)
	ds_write_b32 v115, v114
	s_waitcnt lgkmcnt(0)
	s_mov_b64 exec, s[6:7]
.Lopr_wait:
	s_barrier
	ds_read_b32 v114, v115
	s_waitcnt lgkmcnt(0)
	v_readfirstlane_b32 s12, v114
	v_readfirstlane_b32 s94, v113
.Lopr_flat:
.Lop_item:
	s_cmp_eq_u32 s94, 0
	s_cbranch_scc1 .Lop_flat
	s_barrier
	s_getreg_b32 s8, hwreg(HW_REG_XCC_ID, 0, 4)
	s_lshr_b32 s6, s12, 3
	s_lshl_b32 s6, s6, 3
	s_add_u32 s6, s6, s8
	s_cmp_eq_u32 s18, 0
	s_cbranch_scc0 .Lopx_l1
	s_cmpk_lt_u32 s12, 0x110
	s_cbranch_scc0 .Lop_done
	s_mov_b32 s20, s6
	s_mul_hi_u32 s6, s20, 0x78787879
	s_lshr_b32 s6, s6, 4
	s_mul_i32 s7, s6, 34
	s_sub_u32 s7, s20, s7
	s_cmp_lt_u32 s7, 2
	s_cselect_b32 s21, 8, s6
	s_branch .Lop_decoded

; DI void phase_outproj(const Params& p, int l, char* smem, int tid) {
;     ...
;     f32x16 acc[2][2]; zero_acc<2>(acc);
;     gemm_main<2>(ACC + (size_t)m0 * 1024, 1024, p.WtOut + (size_t)l * 1024 * 1024 + (size_t)n0 * 1024, 1024, 1024, acc, s, tid);
;     u16* O = p.G;
; #pragma unroll
;     for (int mb = 0; mb < 2; mb++)
; #pragma unroll
;       for (int nb = 0; nb < 2; nb++) {
;         const int rowb = m0 + wm * 64 + mb * 32, col = n0 + wn * 64 + nb * 32 + r;
;         const int b = rowb / SEQA, pos0 = rowb % SEQA;
;         const float gate = p.mod[((size_t)l * 9 + ((pos0 < CTXL) ? 8 : b)) * 3072 + 2048 + col];
.Lop_decoded:
.Lop_again:
	s_and_b32 s13, s12, 7
	s_mul_i32 s7, s18, 9
	s_add_u32 s7, s7, s21
	s_mul_i32 s7, s7, 0x3000
	s_lshl_b32 s6, s13, 9
	s_add_u32 s7, s7, s6
	s_add_u32 s7, s7, 0x1d002000
	s_add_u32 s6, s96, s7
	s_addc_u32 s7, s97, 0
	global_load_dwordx4 v[116:119], v111, s[6:7] offset:0
	global_load_dwordx4 v[120:123], v111, s[6:7] offset:32
	global_load_dwordx4 v[124:127], v111, s[6:7] offset:64
	global_load_dwordx4 v[128:131], v111, s[6:7] offset:96
	global_load_dwordx4 v[132:135], v111, s[6:7] offset:128
	global_load_dwordx4 v[136:139], v111, s[6:7] offset:160
	global_load_dwordx4 v[140:143], v111, s[6:7] offset:192
	global_load_dwordx4 v[144:147], v111, s[6:7] offset:224
	s_lshl_b32 s2, s20, 18
	s_add_u32 s4, s90, s2
	s_addc_u32 s5, s91, 0
	s_lshl_b32 s3, s13, 18
	s_add_u32 s8, s14, s3
	s_addc_u32 s9, s15, 0
	s_lshl_b32 s3, s13, 8
	s_add_u32 s2, s2, s3
	s_add_u32 s2, s2, 0x16720000
	s_add_u32 s16, s96, s2
	s_addc_u32 s17, s97, 0
	v_mov_b32_e32 v2, 0
	v_mov_b32_e32 v3, 0
	v_mov_b32_e32 v4, 0
	v_mov_b32_e32 v5, 0
	v_mov_b32_e32 v6, 0
	v_mov_b32_e32 v7, 0
	v_mov_b32_e32 v8, 0
	v_mov_b32_e32 v9, 0
	v_mov_b32_e32 v10, 0
	v_mov_b32_e32 v11, 0
	v_mov_b32_e32 v12, 0
	v_mov_b32_e32 v13, 0
	v_mov_b32_e32 v14, 0
	v_mov_b32_e32 v15, 0
	v_mov_b32_e32 v16, 0
	v_mov_b32_e32 v17, 0
	v_mov_b32_e32 v18, 0
	v_mov_b32_e32 v19, 0
	v_mov_b32_e32 v20, 0
	v_mov_b32_e32 v21, 0
	v_mov_b32_e32 v22, 0
	v_mov_b32_e32 v23, 0
	v_mov_b32_e32 v24, 0
	v_mov_b32_e32 v25, 0
	v_mov_b32_e32 v26, 0
	v_mov_b32_e32 v27, 0
	v_mov_b32_e32 v28, 0
	v_mov_b32_e32 v29, 0
	v_mov_b32_e32 v30, 0
	v_mov_b32_e32 v31, 0
	v_mov_b32_e32 v32, 0
	v_mov_b32_e32 v33, 0
	v_mov_b32_e32 v34, 0
	v_mov_b32_e32 v35, 0
	v_mov_b32_e32 v36, 0
	v_mov_b32_e32 v37, 0
	v_mov_b32_e32 v38, 0
	v_mov_b32_e32 v39, 0
	v_mov_b32_e32 v40, 0
	v_mov_b32_e32 v41, 0
	v_mov_b32_e32 v42, 0
	v_mov_b32_e32 v43, 0
	v_mov_b32_e32 v44, 0
	v_mov_b32_e32 v45, 0
	v_mov_b32_e32 v46, 0
	v_mov_b32_e32 v47, 0
	v_mov_b32_e32 v48, 0
	v_mov_b32_e32 v49, 0
	v_mov_b32_e32 v50, 0
	v_mov_b32_e32 v51, 0
	v_mov_b32_e32 v52, 0
	v_mov_b32_e32 v53, 0
	v_mov_b32_e32 v54, 0
	v_mov_b32_e32 v55, 0
	v_mov_b32_e32 v56, 0
	v_mov_b32_e32 v57, 0
	v_mov_b32_e32 v58, 0
	v_mov_b32_e32 v59, 0
	v_mov_b32_e32 v60, 0
	v_mov_b32_e32 v61, 0
	v_mov_b32_e32 v62, 0
	v_mov_b32_e32 v63, 0
	v_mov_b32_e32 v64, 0
	v_mov_b32_e32 v65, 0
	s_add_u32 m0, s10, 0x0
	s_nop 0
	global_load_lds_dwordx4 v98, s[4:5]
	s_add_u32 m0, s10, 0x400
	s_nop 0
	global_load_lds_dwordx4 v99, s[4:5]
	s_add_u32 m0, s10, 0x800
	s_nop 0
	global_load_lds_dwordx4 v100, s[4:5]
	s_add_u32 m0, s10, 0xc00
	s_nop 0
	global_load_lds_dwordx4 v101, s[4:5]
	s_add_u32 m0, s10, 0x4000
	s_nop 0
	global_load_lds_dwordx4 v98, s[8:9]
	s_add_u32 m0, s10, 0x4400
	s_nop 0
	global_load_lds_dwordx4 v99, s[8:9]
	s_add_u32 m0, s10, 0x4800
	s_nop 0
	global_load_lds_dwordx4 v100, s[8:9]
	s_add_u32 m0, s10, 0x4c00
	s_nop 0
	global_load_lds_dwordx4 v101, s[8:9]
	s_add_u32 s4, s4, 128
	s_addc_u32 s5, s5, 0
	s_add_u32 s8, s8, 128
	s_addc_u32 s9, s9, 0
	s_waitcnt vmcnt(0) lgkmcnt(0)
	s_barrier
	ds_read_b128 v[66:69], v102 offset:0
	ds_read_b128 v[74:77], v106 offset:0
	ds_read_b128 v[70:73], v102 offset:4096
	ds_read_b128 v[78:81], v106 offset:4096
	s_add_u32 m0, s10, 0x8000
	s_nop 0
	global_load_lds_dwordx4 v98, s[4:5]
	s_add_u32 m0, s10, 0x8400
	s_nop 0
	global_load_lds_dwordx4 v99, s[4:5]
	s_add_u32 m0, s10, 0x8800
	s_nop 0
	global_load_lds_dwordx4 v100, s[4:5]
	s_add_u32 m0, s10, 0x8c00
	s_nop 0
	global_load_lds_dwordx4 v101, s[4:5]
	s_add_u32 s4, s4, 128
	s_addc_u32 s5, s5, 0
	s_mov_b32 s11, 7

; DI u16 f2bf(float x) { return (u16)(pack2(x, 0.f) & 0xffffu); }
; DI int crow(int i, int h) { return (i & 3) + 8 * (i >> 2) + 4 * h; }
; DI void phase_outproj(const Params& p, int l, char* smem, int tid) {
;     ...
;     gemm_main<2>(ACC + (size_t)m0 * 1024, 1024, p.WtOut + (size_t)l * 1024 * 1024 + (size_t)n0 * 1024, 1024, 1024, acc, s, tid);
;     u16* O = p.G;
; #pragma unroll
;     for (int mb = 0; mb < 2; mb++)
; #pragma unroll
;       for (int nb = 0; nb < 2; nb++) {
;         const int rowb = m0 + wm * 64 + mb * 32, col = n0 + wn * 64 + nb * 32 + r;
;         const int b = rowb / SEQA, pos0 = rowb % SEQA;
;         const float gate = p.mod[((size_t)l * 9 + ((pos0 < CTXL) ? 8 : b)) * 3072 + 2048 + col];
; #pragma unroll
;         for (int i = 0; i < 16; i++) O[(size_t)(rowb + crow(i, h)) * 1024 + col] = f2bf(gate * acc[mb][nb][i]);
;       }
.Lop_last:
	ds_read_b128 v[82:85], v103 offset:32768
	ds_read_b128 v[90:93], v107 offset:32768
	ds_read_b128 v[86:89], v103 offset:36864
	ds_read_b128 v[94:97], v107 offset:36864
	s_waitcnt lgkmcnt(4)
	v_mfma_f32_32x32x16_bf16 v[2:17], v[74:77], v[66:69], v[2:17]
	v_mfma_f32_32x32x16_bf16 v[18:33], v[78:81], v[66:69], v[18:33]
	v_mfma_f32_32x32x16_bf16 v[34:49], v[74:77], v[70:73], v[34:49]
	v_mfma_f32_32x32x16_bf16 v[50:65], v[78:81], v[70:73], v[50:65]
	ds_read_b128 v[66:69], v104 offset:32768
	ds_read_b128 v[74:77], v108 offset:32768
	ds_read_b128 v[70:73], v104 offset:36864
	ds_read_b128 v[78:81], v108 offset:36864
	s_waitcnt lgkmcnt(4)
	v_mfma_f32_32x32x16_bf16 v[2:17], v[90:93], v[82:85], v[2:17]
	v_mfma_f32_32x32x16_bf16 v[18:33], v[94:97], v[82:85], v[18:33]
	v_mfma_f32_32x32x16_bf16 v[34:49], v[90:93], v[86:89], v[34:49]
	v_mfma_f32_32x32x16_bf16 v[50:65], v[94:97], v[86:89], v[50:65]
	ds_read_b128 v[82:85], v105 offset:32768
	ds_read_b128 v[90:93], v109 offset:32768
	ds_read_b128 v[86:89], v105 offset:36864
	ds_read_b128 v[94:97], v109 offset:36864
	s_waitcnt lgkmcnt(4)
	v_mfma_f32_32x32x16_bf16 v[2:17], v[74:77], v[66:69], v[2:17]
	v_mfma_f32_32x32x16_bf16 v[18:33], v[78:81], v[66:69], v[18:33]
	v_mfma_f32_32x32x16_bf16 v[34:49], v[74:77], v[70:73], v[34:49]
	v_mfma_f32_32x32x16_bf16 v[50:65], v[78:81], v[70:73], v[50:65]
	s_waitcnt vmcnt(0) lgkmcnt(0)
	s_barrier
	v_mfma_f32_32x32x16_bf16 v[2:17], v[90:93], v[82:85], v[2:17]
	v_mfma_f32_32x32x16_bf16 v[18:33], v[94:97], v[82:85], v[18:33]
	v_mfma_f32_32x32x16_bf16 v[34:49], v[90:93], v[86:89], v[34:49]
	v_mfma_f32_32x32x16_bf16 v[50:65], v[94:97], v[86:89], v[50:65]
	s_nop 7
	s_nop 7
	v_mul_f32_e32 v2, v116, v2
	v_mul_f32_e32 v3, v117, v3
	v_mul_f32_e32 v4, v118, v4
	v_mul_f32_e32 v5, v119, v5
	v_mul_f32_e32 v6, v120, v6
	v_mul_f32_e32 v7, v121, v7
	v_mul_f32_e32 v8, v122, v8
	v_mul_f32_e32 v9, v123, v9
	v_mul_f32_e32 v10, v124, v10
	v_mul_f32_e32 v11, v125, v11
	v_mul_f32_e32 v12, v126, v12
	v_mul_f32_e32 v13, v127, v13
	v_mul_f32_e32 v14, v128, v14
	v_mul_f32_e32 v15, v129, v15
	v_mul_f32_e32 v16, v130, v16
	v_mul_f32_e32 v17, v131, v17
	v_mul_f32_e32 v18, v132, v18
	v_mul_f32_e32 v19, v133, v19
	v_mul_f32_e32 v20, v134, v20
	v_mul_f32_e32 v21, v135, v21
	v_mul_f32_e32 v22, v136, v22
	v_mul_f32_e32 v23, v137, v23
	v_mul_f32_e32 v24, v138, v24
	v_mul_f32_e32 v25, v139, v25
	v_mul_f32_e32 v26, v140, v26
	v_mul_f32_e32 v27, v141, v27
	v_mul_f32_e32 v28, v142, v28
	v_mul_f32_e32 v29, v143, v29
	v_mul_f32_e32 v30, v144, v30
	v_mul_f32_e32 v31, v145, v31
	v_mul_f32_e32 v32, v146, v32
	v_mul_f32_e32 v33, v147, v33
	v_mul_f32_e32 v34, v116, v34
	v_mul_f32_e32 v35, v117, v35
	v_mul_f32_e32 v36, v118, v36
	v_mul_f32_e32 v37, v119, v37
	v_mul_f32_e32 v38, v120, v38
	v_mul_f32_e32 v39, v121, v39
	v_mul_f32_e32 v40, v122, v40
	v_mul_f32_e32 v41, v123, v41
	v_mul_f32_e32 v42, v124, v42
	v_mul_f32_e32 v43, v125, v43
	v_mul_f32_e32 v44, v126, v44
	v_mul_f32_e32 v45, v127, v45
	v_mul_f32_e32 v46, v128, v46
	v_mul_f32_e32 v47, v129, v47
	v_mul_f32_e32 v48, v130, v48
	v_mul_f32_e32 v49, v131, v49
	v_mul_f32_e32 v50, v132, v50
	v_mul_f32_e32 v51, v133, v51
	v_mul_f32_e32 v52, v134, v52
	v_mul_f32_e32 v53, v135, v53
	v_mul_f32_e32 v54, v136, v54
	v_mul_f32_e32 v55, v137, v55
	v_mul_f32_e32 v56, v138, v56
	v_mul_f32_e32 v57, v139, v57
	v_mul_f32_e32 v58, v140, v58
	v_mul_f32_e32 v59, v141, v59
	v_mul_f32_e32 v60, v142, v60
	v_mul_f32_e32 v61, v143, v61
	v_mul_f32_e32 v62, v144, v62
	v_mul_f32_e32 v63, v145, v63
	v_mul_f32_e32 v64, v146, v64
	v_mul_f32_e32 v65, v147, v65
	v_cvt_pk_bf16_f32 v156, v2, v3
	v_cvt_pk_bf16_f32 v157, v4, v5
	ds_write_b64 v164, v[156:157] offset:0
	v_cvt_pk_bf16_f32 v158, v6, v7
	v_cvt_pk_bf16_f32 v159, v8, v9
	ds_write_b64 v164, v[158:159] offset:16
	v_cvt_pk_bf16_f32 v160, v10, v11
	v_cvt_pk_bf16_f32 v161, v12, v13
	ds_write_b64 v164, v[160:161] offset:32
	v_cvt_pk_bf16_f32 v162, v14, v15
	v_cvt_pk_bf16_f32 v163, v16, v17
	ds_write_b64 v164, v[162:163] offset:48
	v_cvt_pk_bf16_f32 v156, v18, v19
	v_cvt_pk_bf16_f32 v157, v20, v21
	ds_write_b64 v164, v[156:157] offset:64
	v_cvt_pk_bf16_f32 v158, v22, v23
	v_cvt_pk_bf16_f32 v159, v24, v25
	ds_write_b64 v164, v[158:159] offset:80
	v_cvt_pk_bf16_f32 v160, v26, v27
	v_cvt_pk_bf16_f32 v161, v28, v29
	ds_write_b64 v164, v[160:161] offset:96
	v_cvt_pk_bf16_f32 v162, v30, v31
	v_cvt_pk_bf16_f32 v163, v32, v33
	ds_write_b64 v164, v[162:163] offset:112
	v_cvt_pk_bf16_f32 v156, v34, v35
	v_cvt_pk_bf16_f32 v157, v36, v37
	ds_write_b64 v164, v[156:157] offset:4608
	v_cvt_pk_bf16_f32 v158, v38, v39
	v_cvt_pk_bf16_f32 v159, v40, v41
	ds_write_b64 v164, v[158:159] offset:4624
	v_cvt_pk_bf16_f32 v160, v42, v43
	v_cvt_pk_bf16_f32 v161, v44, v45
	ds_write_b64 v164, v[160:161] offset:4640
	v_cvt_pk_bf16_f32 v162, v46, v47
	v_cvt_pk_bf16_f32 v163, v48, v49
	ds_write_b64 v164, v[162:163] offset:4656
	v_cvt_pk_bf16_f32 v156, v50, v51
	v_cvt_pk_bf16_f32 v157, v52, v53
	ds_write_b64 v164, v[156:157] offset:4672
	v_cvt_pk_bf16_f32 v158, v54, v55
	v_cvt_pk_bf16_f32 v159, v56, v57
	ds_write_b64 v164, v[158:159] offset:4688
	v_cvt_pk_bf16_f32 v160, v58, v59
	v_cvt_pk_bf16_f32 v161, v60, v61
	ds_write_b64 v164, v[160:161] offset:4704
	v_cvt_pk_bf16_f32 v162, v62, v63
	v_cvt_pk_bf16_f32 v163, v64, v65
	ds_write_b64 v164, v[162:163] offset:4720
	ds_read_b128 v[66:69], v165 offset:0
	ds_read_b128 v[70:73], v165 offset:1152
	ds_read_b128 v[74:77], v165 offset:2304
	ds_read_b128 v[78:81], v165 offset:3456
	ds_read_b128 v[82:85], v165 offset:4608
	ds_read_b128 v[86:89], v165 offset:5760
	ds_read_b128 v[90:93], v165 offset:6912
	ds_read_b128 v[94:97], v165 offset:8064
	s_waitcnt lgkmcnt(7)
	global_store_dwordx4 v166, v[66:69], s[16:17]
	s_add_u32 s16, s16, 0x4000
	s_addc_u32 s17, s17, 0
	s_waitcnt lgkmcnt(6)
	global_store_dwordx4 v166, v[70:73], s[16:17]
	s_add_u32 s16, s16, 0x4000
	s_addc_u32 s17, s17, 0
	s_waitcnt lgkmcnt(5)
	global_store_dwordx4 v166, v[74:77], s[16:17]
	s_add_u32 s16, s16, 0x4000
	s_addc_u32 s17, s17, 0
	s_waitcnt lgkmcnt(4)
	global_store_dwordx4 v166, v[78:81], s[16:17]
	s_add_u32 s16, s16, 0x4000
	s_addc_u32 s17, s17, 0
	s_waitcnt lgkmcnt(3)
	global_store_dwordx4 v166, v[82:85], s[16:17]
	s_add_u32 s16, s16, 0x4000
	s_addc_u32 s17, s17, 0
	s_waitcnt lgkmcnt(2)
	global_store_dwordx4 v166, v[86:89], s[16:17]
	s_add_u32 s16, s16, 0x4000
	s_addc_u32 s17, s17, 0
	s_waitcnt lgkmcnt(1)
	global_store_dwordx4 v166, v[90:93], s[16:17]
	s_add_u32 s16, s16, 0x4000
	s_addc_u32 s17, s17, 0
	s_waitcnt lgkmcnt(0)
	global_store_dwordx4 v166, v[94:97], s[16:17]
	s_cmp_eq_u32 s94, 0
	s_cbranch_scc1 .Lop_lbflat
	s_add_u32 s12, s12, s94
	s_branch .Lop_item
